# RWKV producers wave-sum bcast stages fused with placeholder nops deleted (hazard-checked), 48 fewer instrs per tile
# speedup vs baseline: 1.0011x; 1.0011x over previous
.LBB0_577:
	s_and_saveexec_b64 s[0:1], s[4:5]
	s_xor_b64 s[20:21], exec, s[0:1]
	s_cbranch_execz .LBB0_595
	s_cmp_lg_u32 s18, 0
	s_cselect_b64 s[22:23], -1, 0
	s_cmp_eq_u32 s18, 0
	s_cbranch_scc1 .LBB0_580
	s_andn2_b32 s1, 1, s25
	s_lshl_b32 s0, s1, 12
	s_add_i32 s27, s0, 0
	v_lshlrev_b32_e32 v1, 2, v85
	v_add_u32_e32 v2, s27, v1
	ds_read2st64_b32 v[42:43], v2 offset0:192 offset1:224
	s_mul_i32 s0, s1, 0x5000
	s_add_i32 s26, s27, s0
	v_add_u32_e32 v1, s26, v1
	ds_read_b32 v72, v1 offset:20480
	s_waitcnt lgkmcnt(1)
	v_add_f32_dpp v2, v42, v42 quad_perm:[1,0,3,2] row_mask:0xf bank_mask:0xf bound_ctrl:1
	v_mul_f32_e32 v1, 0xbfb8aa3b, v43
	v_mov_b32_e32 v3, v0
	v_add_f32_dpp v2, v2, v2 quad_perm:[2,3,0,1] row_mask:0xf bank_mask:0xf bound_ctrl:1
	v_exp_f32_e32 v1, v1
	s_lshl_b32 s1, s1, 6
	v_add_f32_dpp v2, v2, v2 row_half_mirror row_mask:0xf bank_mask:0xf bound_ctrl:1
	s_add_i32 s1, s1, 0
	v_add_f32_e32 v1, 1.0, v1
	v_add_f32_dpp v2, v2, v2 row_mirror row_mask:0xf bank_mask:0xf bound_ctrl:1
	v_rcp_f32_e32 v74, v1
	v_lshlrev_b32_e32 v1, 2, v86
	v_add_f32_dpp v2, v2, v2 row_bcast:15 row_mask:0xa bank_mask:0xf
	s_mov_b32 s30, 0x3c800000
	v_mov_b32_e32 v36, v42
	v_add_f32_dpp v2, v2, v2 row_bcast:31 row_mask:0xc bank_mask:0xf
	s_nop 0
	v_readlane_b32 s0, v2, 63
	v_lshl_add_u32 v2, v84, 2, s1
	v_add_u32_e32 v149, 0x10000, v2
	v_add_u32_e32 v2, s27, v1
	ds_read2st64_b32 v[150:151], v2 offset0:192 offset1:224
	v_mov_b32_e32 v40, v0
	s_mov_b32 s34, 0x45800000
	v_add_u32_e32 v1, s26, v1
	ds_read_b32 v73, v1 offset:20480
	s_waitcnt lgkmcnt(1)
	v_add_f32_dpp v2, v150, v150 quad_perm:[1,0,3,2] row_mask:0xf bank_mask:0xf bound_ctrl:1
	v_mov_b32_e32 v37, v150
	v_mov_b32_e32 v150, v43
	v_add_f32_dpp v2, v2, v2 quad_perm:[2,3,0,1] row_mask:0xf bank_mask:0xf bound_ctrl:1
	s_nop 1
	v_add_f32_dpp v2, v2, v2 row_half_mirror row_mask:0xf bank_mask:0xf bound_ctrl:1
	s_nop 1
	v_add_f32_dpp v2, v2, v2 row_mirror row_mask:0xf bank_mask:0xf bound_ctrl:1
	s_nop 1
	v_add_f32_dpp v2, v2, v2 row_bcast:15 row_mask:0xa bank_mask:0xf
	s_nop 1
	v_add_f32_dpp v2, v2, v2 row_bcast:31 row_mask:0xc bank_mask:0xf
	s_nop 0
	v_readlane_b32 s1, v2, 63
	v_mov_b64_e32 v[2:3], s[30:31]
	s_mov_b32 s30, 0x3a27c5ac
	v_pk_fma_f32 v[36:37], s[0:1], v[2:3], v[36:37] op_sel_hi:[1,0,1] neg_lo:[1,0,0] neg_hi:[1,0,0]
	s_nop 0
	v_pk_mul_f32 v[38:39], v[36:37], v[36:37]
	s_nop 1
	v_add_f32_dpp v38, v38, v38 quad_perm:[1,0,3,2] row_mask:0xf bank_mask:0xf bound_ctrl:1
	s_nop 1
	v_add_f32_dpp v38, v38, v38 quad_perm:[2,3,0,1] row_mask:0xf bank_mask:0xf bound_ctrl:1
	s_nop 1
	v_add_f32_dpp v38, v38, v38 row_half_mirror row_mask:0xf bank_mask:0xf bound_ctrl:1
	s_nop 1
	v_add_f32_dpp v38, v38, v38 row_mirror row_mask:0xf bank_mask:0xf bound_ctrl:1
	s_nop 1
	v_add_f32_dpp v38, v38, v38 row_bcast:15 row_mask:0xa bank_mask:0xf
	s_nop 1
	v_add_f32_dpp v38, v38, v38 row_bcast:31 row_mask:0xc bank_mask:0xf
	v_mov_b64_e32 v[40:41], s[30:31]
	v_readlane_b32 s0, v38, 63
	v_add_f32_dpp v38, v39, v39 quad_perm:[1,0,3,2] row_mask:0xf bank_mask:0xf bound_ctrl:1
	v_mov_b32_e32 v39, v0
	s_movk_i32 s30, 0x7fff
	v_add_f32_dpp v38, v38, v38 quad_perm:[2,3,0,1] row_mask:0xf bank_mask:0xf bound_ctrl:1
	s_mov_b32 s31, 0x7060302
	s_nop 0
	v_add_f32_dpp v38, v38, v38 row_half_mirror row_mask:0xf bank_mask:0xf bound_ctrl:1
	s_nop 1
	v_add_f32_dpp v38, v38, v38 row_mirror row_mask:0xf bank_mask:0xf bound_ctrl:1
	s_nop 1
	v_add_f32_dpp v38, v38, v38 row_bcast:15 row_mask:0xa bank_mask:0xf
	s_nop 1
	v_add_f32_dpp v38, v38, v38 row_bcast:31 row_mask:0xc bank_mask:0xf
	s_nop 0
	v_readlane_b32 s1, v38, 63
	s_nop 1
	v_pk_fma_f32 v[38:39], s[0:1], v[2:3], v[40:41] op_sel_hi:[1,0,0]
	s_nop 0
	v_mul_f32_e32 v42, 0x4b800000, v38
	v_cmp_gt_f32_e64 s[0:1], s72, v38
	v_cmp_gt_f32_e32 vcc, s72, v39
	s_nop 0
	v_cndmask_b32_e64 v38, v38, v42, s[0:1]
	v_mul_f32_e32 v42, 0x4b800000, v39
	v_cndmask_b32_e32 v39, v39, v42, vcc
	v_rsq_f32_e32 v38, v38
	v_rsq_f32_e32 v39, v39
	s_nop 0
	v_pk_mul_f32 v[152:153], v[38:39], s[34:35] op_sel_hi:[1,0]
	s_nop 0
	v_cndmask_b32_e32 v39, v39, v153, vcc
	v_cndmask_b32_e64 v38, v38, v152, s[0:1]
	v_pk_mul_f32 v[36:37], v[36:37], v[38:39]
	s_nop 0
	v_pk_fma_f32 v[152:153], v[50:51], v[36:37], v[48:49]
	ds_read_b128 v[36:39], v149
	v_mul_f32_e32 v1, 0xbfb8aa3b, v151
	v_exp_f32_e32 v1, v1
	s_waitcnt lgkmcnt(0)
	v_pk_fma_f32 v[36:37], v[36:37], v[72:73], v[152:153]
	v_add_f32_e32 v1, 1.0, v1
	v_rcp_f32_e32 v75, v1
	v_mov_b32_e32 v73, v0
	v_pk_mul_f32 v[42:43], v[150:151], v[74:75]
	s_nop 0
	v_pk_mul_f32 v[36:37], v[42:43], v[36:37]
	v_mov_b32_e32 v43, v0
	v_and_b32_sdwa v1, v37, v190 dst_sel:DWORD dst_unused:UNUSED_PAD src0_sel:WORD_1 src1_sel:DWORD
	v_and_b32_sdwa v42, v36, v190 dst_sel:DWORD dst_unused:UNUSED_PAD src0_sel:WORD_1 src1_sel:DWORD
	v_add3_u32 v36, v36, v42, s30
	v_add3_u32 v1, v37, v1, s30
	v_perm_b32 v149, v1, v36, s31
	v_lshlrev_b32_e32 v1, 2, v87
	v_add_u32_e32 v36, s27, v1
	ds_read2st64_b32 v[36:37], v36 offset0:192 offset1:224
	v_add_u32_e32 v1, s26, v1
	s_waitcnt lgkmcnt(0)
	v_mov_b32_e32 v150, v36
	v_add_f32_dpp v42, v36, v36 quad_perm:[1,0,3,2] row_mask:0xf bank_mask:0xf bound_ctrl:1
	s_nop 1
	v_add_f32_dpp v42, v42, v42 quad_perm:[2,3,0,1] row_mask:0xf bank_mask:0xf bound_ctrl:1
	s_nop 1
	v_add_f32_dpp v42, v42, v42 row_half_mirror row_mask:0xf bank_mask:0xf bound_ctrl:1
	s_nop 1
	v_add_f32_dpp v42, v42, v42 row_mirror row_mask:0xf bank_mask:0xf bound_ctrl:1
	s_nop 1
	v_add_f32_dpp v42, v42, v42 row_bcast:15 row_mask:0xa bank_mask:0xf
	s_nop 1
	v_add_f32_dpp v42, v42, v42 row_bcast:31 row_mask:0xc bank_mask:0xf
	s_nop 0
	v_readlane_b32 s0, v42, 63
	ds_read_b32 v42, v1 offset:20480
	v_mul_f32_e32 v1, 0xbfb8aa3b, v37
	v_exp_f32_e32 v1, v1
	s_nop 0
	v_add_f32_e32 v1, 1.0, v1
	v_rcp_f32_e32 v72, v1
	v_lshlrev_b32_e32 v1, 2, v88
	v_add_u32_e32 v43, s27, v1
	ds_read2st64_b32 v[74:75], v43 offset0:192 offset1:224
	v_add_u32_e32 v1, s26, v1
	s_waitcnt lgkmcnt(0)
	v_mov_b32_e32 v151, v74
	v_add_f32_dpp v43, v74, v74 quad_perm:[1,0,3,2] row_mask:0xf bank_mask:0xf bound_ctrl:1
	v_mov_b32_e32 v74, v37
	s_nop 0
	v_add_f32_dpp v43, v43, v43 quad_perm:[2,3,0,1] row_mask:0xf bank_mask:0xf bound_ctrl:1
	s_nop 1
	v_add_f32_dpp v43, v43, v43 row_half_mirror row_mask:0xf bank_mask:0xf bound_ctrl:1
	s_nop 1
	v_add_f32_dpp v43, v43, v43 row_mirror row_mask:0xf bank_mask:0xf bound_ctrl:1
	s_nop 1
	v_add_f32_dpp v43, v43, v43 row_bcast:15 row_mask:0xa bank_mask:0xf
	s_nop 1
	v_add_f32_dpp v43, v43, v43 row_bcast:31 row_mask:0xc bank_mask:0xf
	s_nop 0
	v_readlane_b32 s1, v43, 63
	v_mov_b32_e32 v43, v0
	s_nop 0
	v_pk_fma_f32 v[150:151], s[0:1], v[2:3], v[150:151] op_sel_hi:[1,0,1] neg_lo:[1,0,0] neg_hi:[1,0,0]
	s_nop 0
	v_pk_mul_f32 v[152:153], v[150:151], v[150:151]
	s_nop 1
	v_add_f32_dpp v36, v152, v152 quad_perm:[1,0,3,2] row_mask:0xf bank_mask:0xf bound_ctrl:1
	s_nop 1
	v_add_f32_dpp v36, v36, v36 quad_perm:[2,3,0,1] row_mask:0xf bank_mask:0xf bound_ctrl:1
	s_nop 1
	v_add_f32_dpp v36, v36, v36 row_half_mirror row_mask:0xf bank_mask:0xf bound_ctrl:1
	s_nop 1
	v_add_f32_dpp v36, v36, v36 row_mirror row_mask:0xf bank_mask:0xf bound_ctrl:1
	s_nop 1
	v_add_f32_dpp v36, v36, v36 row_bcast:15 row_mask:0xa bank_mask:0xf
	s_nop 1
	v_add_f32_dpp v36, v36, v36 row_bcast:31 row_mask:0xc bank_mask:0xf
	s_nop 0
	v_readlane_b32 s0, v36, 63
	v_add_f32_dpp v36, v153, v153 quad_perm:[1,0,3,2] row_mask:0xf bank_mask:0xf bound_ctrl:1
	s_nop 1
	v_add_f32_dpp v36, v36, v36 quad_perm:[2,3,0,1] row_mask:0xf bank_mask:0xf bound_ctrl:1
	s_nop 1
	v_add_f32_dpp v36, v36, v36 row_half_mirror row_mask:0xf bank_mask:0xf bound_ctrl:1
	s_nop 1
	v_add_f32_dpp v36, v36, v36 row_mirror row_mask:0xf bank_mask:0xf bound_ctrl:1
	s_nop 1
	v_add_f32_dpp v36, v36, v36 row_bcast:15 row_mask:0xa bank_mask:0xf
	s_nop 1
	v_add_f32_dpp v36, v36, v36 row_bcast:31 row_mask:0xc bank_mask:0xf
	ds_read_b32 v43, v1 offset:20480
	v_readlane_b32 s1, v36, 63
	v_mul_f32_e32 v1, 0xbfb8aa3b, v75
	v_exp_f32_e32 v1, v1
	v_pk_fma_f32 v[2:3], s[0:1], v[2:3], v[40:41] op_sel_hi:[1,0,0]
	v_add_f32_e32 v1, 1.0, v1
	v_mul_f32_e32 v36, 0x4b800000, v2
	v_cmp_gt_f32_e64 s[0:1], s72, v2
	v_cmp_gt_f32_e32 vcc, s72, v3
	v_rcp_f32_e32 v73, v1
	v_cndmask_b32_e64 v2, v2, v36, s[0:1]
	v_mul_f32_e32 v36, 0x4b800000, v3
	v_cndmask_b32_e32 v3, v3, v36, vcc
	v_rsq_f32_e32 v2, v2
	v_rsq_f32_e32 v3, v3
	v_pk_mul_f32 v[36:37], v[74:75], v[72:73]
	v_pk_mul_f32 v[40:41], v[2:3], s[34:35] op_sel_hi:[1,0]
	s_nop 0
	v_cndmask_b32_e32 v3, v3, v41, vcc
	v_cndmask_b32_e64 v2, v2, v40, s[0:1]
	v_pk_mul_f32 v[2:3], v[150:151], v[2:3]
	s_nop 0
	v_pk_fma_f32 v[2:3], v[50:51], v[2:3], v[48:49]
	s_waitcnt lgkmcnt(0)
	v_pk_fma_f32 v[2:3], v[38:39], v[42:43], v[2:3]
	s_nop 0
	v_pk_mul_f32 v[2:3], v[36:37], v[2:3]
	s_nop 0
	v_and_b32_sdwa v1, v3, v190 dst_sel:DWORD dst_unused:UNUSED_PAD src0_sel:WORD_1 src1_sel:DWORD
	v_and_b32_sdwa v36, v2, v190 dst_sel:DWORD dst_unused:UNUSED_PAD src0_sel:WORD_1 src1_sel:DWORD
	v_add3_u32 v2, v2, v36, s30
	v_add3_u32 v1, v3, v1, s30
	v_perm_b32 v150, v1, v2, s31

.LBB0_624:
	s_or_b64 exec, exec, s[0:1]
	s_waitcnt lgkmcnt(0)
	s_barrier
	s_and_saveexec_b64 s[0:1], s[4:5]
	s_xor_b64 s[0:1], exec, s[0:1]
	s_cbranch_execz .LBB0_635
	s_cmp_eq_u32 s18, 0xee2000
	s_cbranch_scc1 .LBB0_635
	s_andn2_b32 s20, 1, s25
	s_mul_i32 s21, s20, 0x6000
	s_add_i32 s23, s21, 0
	v_lshl_add_u32 v1, v85, 2, s23
	ds_read2st64_b32 v[2:3], v1 offset0:16 offset1:32
	v_mov_b32_e32 v40, v0
	s_lshl_b32 s22, s20, 4
	s_waitcnt lgkmcnt(0)
	v_add_f32_e32 v2, v82, v2
	v_mul_f32_e32 v2, 0xbfb8aa3b, v2
	v_exp_f32_e32 v2, v2
	v_add_f32_e32 v3, v81, v3
	v_add_f32_e32 v2, 1.0, v2
	v_rcp_f32_e32 v2, v2
	s_nop 0
	v_mul_f32_e32 v2, 0xbf1b4598, v2
	v_mul_f32_e32 v2, 0x3fb8aa3b, v2
	v_exp_f32_e32 v36, v2
	v_mul_f32_e32 v2, 0xbfb8aa3b, v3
	v_exp_f32_e32 v2, v2
	s_nop 0
	v_add_f32_e32 v2, 1.0, v2
	v_rcp_f32_e32 v37, v2
	ds_read2st64_b32 v[2:3], v1 offset0:48 offset1:64
	s_waitcnt lgkmcnt(0)
	v_mul_f32_e32 v38, v80, v2
	v_mul_f32_e32 v39, v38, v38
	s_nop 1
	v_mov_b32_dpp v39, v39 quad_perm:[1,0,3,2] row_mask:0xf bank_mask:0xf bound_ctrl:1
	v_fmac_f32_e32 v39, v38, v38
	s_nop 1
	v_add_f32_dpp v39, v39, v39 quad_perm:[2,3,0,1] row_mask:0xf bank_mask:0xf bound_ctrl:1
	s_nop 1
	v_add_f32_dpp v39, v39, v39 row_half_mirror row_mask:0xf bank_mask:0xf bound_ctrl:1
	s_nop 1
	v_add_f32_dpp v39, v39, v39 row_mirror row_mask:0xf bank_mask:0xf bound_ctrl:1
	s_nop 1
	v_add_f32_dpp v39, v39, v39 row_bcast:15 row_mask:0xa bank_mask:0xf
	s_nop 1
	v_add_f32_dpp v39, v39, v39 row_bcast:31 row_mask:0xc bank_mask:0xf
	s_nop 0
	v_readlane_b32 s20, v39, 63
	s_nop 1
	v_add_f32_e32 v39, s20, v184
	v_cmp_gt_f32_e32 vcc, s72, v39
	v_mul_f32_e32 v40, 0x4b800000, v39
	s_nop 0
	v_cndmask_b32_e32 v39, v39, v40, vcc
	v_rsq_f32_e32 v39, v39
	s_nop 0
	v_mul_f32_e32 v40, 0x45800000, v39
	v_cndmask_b32_e32 v39, v39, v40, vcc
	v_mul_f32_e32 v38, v38, v39
	v_add_f32_e32 v39, -1.0, v37
	v_fma_f32 v39, v79, v39, 1.0
	v_mul_f32_e32 v2, v2, v39
	v_mul_f32_e32 v3, v3, v2
	v_mul_f32_e32 v39, v78, v3
	ds_write2st64_b32 v1, v38, v36 offset1:16
	s_nop 0
	v_mov_b32_dpp v39, v39 quad_perm:[1,0,3,2] row_mask:0xf bank_mask:0xf bound_ctrl:1
	v_fmac_f32_e32 v39, v78, v3
	s_nop 1
	v_add_f32_dpp v3, v39, v39 quad_perm:[2,3,0,1] row_mask:0xf bank_mask:0xf bound_ctrl:1
	v_mov_b32_e32 v39, v0
	s_nop 0
	v_add_f32_dpp v3, v3, v3 row_half_mirror row_mask:0xf bank_mask:0xf bound_ctrl:1
	s_nop 1
	v_add_f32_dpp v3, v3, v3 row_mirror row_mask:0xf bank_mask:0xf bound_ctrl:1
	s_nop 1
	v_add_f32_dpp v3, v3, v3 row_bcast:15 row_mask:0xa bank_mask:0xf
	s_nop 1
	v_add_f32_dpp v3, v3, v3 row_bcast:31 row_mask:0xc bank_mask:0xf
	s_nop 0
	v_readlane_b32 s26, v3, 63
	v_mul_f32_e32 v3, v37, v38
	ds_write2st64_b32 v1, v3, v2 offset0:32 offset1:48
	s_and_saveexec_b64 s[20:21], s[16:17]
	v_lshl_add_u32 v1, s22, 2, v106
	v_mov_b32_e32 v2, s26
	ds_write_b32 v1, v2
	s_or_b64 exec, exec, s[20:21]
	v_lshl_add_u32 v1, v86, 2, s23
	ds_read2st64_b32 v[2:3], v1 offset0:16 offset1:32
	v_mov_b32_e32 v40, v0
	s_waitcnt lgkmcnt(0)
	v_add_f32_e32 v2, v82, v2
	v_mul_f32_e32 v2, 0xbfb8aa3b, v2
	v_exp_f32_e32 v2, v2
	v_add_f32_e32 v3, v81, v3
	v_add_f32_e32 v2, 1.0, v2
	v_rcp_f32_e32 v2, v2
	s_nop 0
	v_mul_f32_e32 v2, 0xbf1b4598, v2
	v_mul_f32_e32 v2, 0x3fb8aa3b, v2
	v_exp_f32_e32 v36, v2
	v_mul_f32_e32 v2, 0xbfb8aa3b, v3
	v_exp_f32_e32 v2, v2
	s_nop 0
	v_add_f32_e32 v2, 1.0, v2
	v_rcp_f32_e32 v37, v2
	ds_read2st64_b32 v[2:3], v1 offset0:48 offset1:64
	s_waitcnt lgkmcnt(0)
	v_mul_f32_e32 v38, v80, v2
	v_mul_f32_e32 v39, v38, v38
	s_nop 1
	v_mov_b32_dpp v39, v39 quad_perm:[1,0,3,2] row_mask:0xf bank_mask:0xf bound_ctrl:1
	v_fmac_f32_e32 v39, v38, v38
	s_nop 1
	v_add_f32_dpp v39, v39, v39 quad_perm:[2,3,0,1] row_mask:0xf bank_mask:0xf bound_ctrl:1
	s_nop 1
	v_add_f32_dpp v39, v39, v39 row_half_mirror row_mask:0xf bank_mask:0xf bound_ctrl:1
	s_nop 1
	v_add_f32_dpp v39, v39, v39 row_mirror row_mask:0xf bank_mask:0xf bound_ctrl:1
	s_nop 1
	v_add_f32_dpp v39, v39, v39 row_bcast:15 row_mask:0xa bank_mask:0xf
	s_nop 1
	v_add_f32_dpp v39, v39, v39 row_bcast:31 row_mask:0xc bank_mask:0xf
	s_nop 0
	v_readlane_b32 s20, v39, 63
	s_nop 1
	v_add_f32_e32 v39, s20, v184
	v_cmp_gt_f32_e32 vcc, s72, v39
	v_mul_f32_e32 v40, 0x4b800000, v39
	s_nop 0
	v_cndmask_b32_e32 v39, v39, v40, vcc
	v_rsq_f32_e32 v39, v39
	s_nop 0
	v_mul_f32_e32 v40, 0x45800000, v39
	v_cndmask_b32_e32 v39, v39, v40, vcc
	v_mul_f32_e32 v38, v38, v39
	v_add_f32_e32 v39, -1.0, v37
	v_fma_f32 v39, v79, v39, 1.0
	v_mul_f32_e32 v2, v2, v39
	v_mul_f32_e32 v3, v3, v2
	v_mul_f32_e32 v39, v78, v3
	ds_write2st64_b32 v1, v38, v36 offset1:16
	s_nop 0
	v_mov_b32_dpp v39, v39 quad_perm:[1,0,3,2] row_mask:0xf bank_mask:0xf bound_ctrl:1
	v_fmac_f32_e32 v39, v78, v3
	s_nop 1
	v_add_f32_dpp v3, v39, v39 quad_perm:[2,3,0,1] row_mask:0xf bank_mask:0xf bound_ctrl:1
	v_mov_b32_e32 v39, v0
	s_nop 0
	v_add_f32_dpp v3, v3, v3 row_half_mirror row_mask:0xf bank_mask:0xf bound_ctrl:1
	s_nop 1
	v_add_f32_dpp v3, v3, v3 row_mirror row_mask:0xf bank_mask:0xf bound_ctrl:1
	s_nop 1
	v_add_f32_dpp v3, v3, v3 row_bcast:15 row_mask:0xa bank_mask:0xf
	s_nop 1
	v_add_f32_dpp v3, v3, v3 row_bcast:31 row_mask:0xc bank_mask:0xf
	s_nop 0
	v_readlane_b32 s26, v3, 63
	v_mul_f32_e32 v3, v37, v38
	ds_write2st64_b32 v1, v3, v2 offset0:32 offset1:48
	s_and_saveexec_b64 s[20:21], s[16:17]
	v_lshl_add_u32 v1, s22, 2, v144
	v_mov_b32_e32 v2, s26
	ds_write_b32 v1, v2
	s_or_b64 exec, exec, s[20:21]
	v_lshl_add_u32 v1, v87, 2, s23
	ds_read2st64_b32 v[2:3], v1 offset0:16 offset1:32
	v_mov_b32_e32 v40, v0
	s_waitcnt lgkmcnt(0)
	v_add_f32_e32 v2, v82, v2
	v_mul_f32_e32 v2, 0xbfb8aa3b, v2
	v_exp_f32_e32 v2, v2
	v_add_f32_e32 v3, v81, v3
	v_add_f32_e32 v2, 1.0, v2
	v_rcp_f32_e32 v2, v2
	s_nop 0
	v_mul_f32_e32 v2, 0xbf1b4598, v2
	v_mul_f32_e32 v2, 0x3fb8aa3b, v2
	v_exp_f32_e32 v36, v2
	v_mul_f32_e32 v2, 0xbfb8aa3b, v3
	v_exp_f32_e32 v2, v2
	s_nop 0
	v_add_f32_e32 v2, 1.0, v2
	v_rcp_f32_e32 v37, v2
	ds_read2st64_b32 v[2:3], v1 offset0:48 offset1:64
	s_waitcnt lgkmcnt(0)
	v_mul_f32_e32 v38, v80, v2
	v_mul_f32_e32 v39, v38, v38
	s_nop 1
	v_mov_b32_dpp v39, v39 quad_perm:[1,0,3,2] row_mask:0xf bank_mask:0xf bound_ctrl:1
	v_fmac_f32_e32 v39, v38, v38
	s_nop 1
	v_add_f32_dpp v39, v39, v39 quad_perm:[2,3,0,1] row_mask:0xf bank_mask:0xf bound_ctrl:1
	s_nop 1
	v_add_f32_dpp v39, v39, v39 row_half_mirror row_mask:0xf bank_mask:0xf bound_ctrl:1
	s_nop 1
	v_add_f32_dpp v39, v39, v39 row_mirror row_mask:0xf bank_mask:0xf bound_ctrl:1
	s_nop 1
	v_add_f32_dpp v39, v39, v39 row_bcast:15 row_mask:0xa bank_mask:0xf
	s_nop 1
	v_add_f32_dpp v39, v39, v39 row_bcast:31 row_mask:0xc bank_mask:0xf
	s_nop 0
	v_readlane_b32 s20, v39, 63
	s_nop 1
	v_add_f32_e32 v39, s20, v184
	v_cmp_gt_f32_e32 vcc, s72, v39
	v_mul_f32_e32 v40, 0x4b800000, v39
	s_nop 0
	v_cndmask_b32_e32 v39, v39, v40, vcc
	v_rsq_f32_e32 v39, v39
	s_nop 0
	v_mul_f32_e32 v40, 0x45800000, v39
	v_cndmask_b32_e32 v39, v39, v40, vcc
	v_mul_f32_e32 v38, v38, v39
	v_add_f32_e32 v39, -1.0, v37
	v_fma_f32 v39, v79, v39, 1.0
	v_mul_f32_e32 v2, v2, v39
	v_mul_f32_e32 v3, v3, v2
	v_mul_f32_e32 v39, v78, v3
	ds_write2st64_b32 v1, v38, v36 offset1:16
	s_nop 0
	v_mov_b32_dpp v39, v39 quad_perm:[1,0,3,2] row_mask:0xf bank_mask:0xf bound_ctrl:1
	v_fmac_f32_e32 v39, v78, v3
	s_nop 1
	v_add_f32_dpp v3, v39, v39 quad_perm:[2,3,0,1] row_mask:0xf bank_mask:0xf bound_ctrl:1
	v_mov_b32_e32 v39, v0
	s_nop 0
	v_add_f32_dpp v3, v3, v3 row_half_mirror row_mask:0xf bank_mask:0xf bound_ctrl:1
	s_nop 1
	v_add_f32_dpp v3, v3, v3 row_mirror row_mask:0xf bank_mask:0xf bound_ctrl:1
	s_nop 1
	v_add_f32_dpp v3, v3, v3 row_bcast:15 row_mask:0xa bank_mask:0xf
	s_nop 1
	v_add_f32_dpp v3, v3, v3 row_bcast:31 row_mask:0xc bank_mask:0xf
	s_nop 0
	v_readlane_b32 s26, v3, 63
	v_mul_f32_e32 v3, v37, v38
	ds_write2st64_b32 v1, v3, v2 offset0:32 offset1:48
	s_and_saveexec_b64 s[20:21], s[16:17]
	v_lshl_add_u32 v1, s22, 2, v145
	v_mov_b32_e32 v2, s26
	ds_write_b32 v1, v2
	s_or_b64 exec, exec, s[20:21]
	v_lshl_add_u32 v1, v88, 2, s23
	ds_read2st64_b32 v[2:3], v1 offset0:16 offset1:32
	v_mov_b32_e32 v40, v0
	s_waitcnt lgkmcnt(0)
	v_add_f32_e32 v2, v82, v2
	v_mul_f32_e32 v2, 0xbfb8aa3b, v2
	v_exp_f32_e32 v2, v2
	v_add_f32_e32 v3, v81, v3
	v_add_f32_e32 v2, 1.0, v2
	v_rcp_f32_e32 v2, v2
	s_nop 0
	v_mul_f32_e32 v2, 0xbf1b4598, v2
	v_mul_f32_e32 v2, 0x3fb8aa3b, v2
	v_exp_f32_e32 v36, v2
	v_mul_f32_e32 v2, 0xbfb8aa3b, v3
	v_exp_f32_e32 v2, v2
	s_nop 0
	v_add_f32_e32 v2, 1.0, v2
	v_rcp_f32_e32 v37, v2
	ds_read2st64_b32 v[2:3], v1 offset0:48 offset1:64
	s_waitcnt lgkmcnt(0)
	v_mul_f32_e32 v38, v80, v2
	v_mul_f32_e32 v39, v38, v38
	s_nop 1
	v_mov_b32_dpp v39, v39 quad_perm:[1,0,3,2] row_mask:0xf bank_mask:0xf bound_ctrl:1
	v_fmac_f32_e32 v39, v38, v38
	s_nop 1
	v_add_f32_dpp v39, v39, v39 quad_perm:[2,3,0,1] row_mask:0xf bank_mask:0xf bound_ctrl:1
	s_nop 1
	v_add_f32_dpp v39, v39, v39 row_half_mirror row_mask:0xf bank_mask:0xf bound_ctrl:1
	s_nop 1
	v_add_f32_dpp v39, v39, v39 row_mirror row_mask:0xf bank_mask:0xf bound_ctrl:1
	s_nop 1
	v_add_f32_dpp v39, v39, v39 row_bcast:15 row_mask:0xa bank_mask:0xf
	s_nop 1
	v_add_f32_dpp v39, v39, v39 row_bcast:31 row_mask:0xc bank_mask:0xf
	s_nop 0
	v_readlane_b32 s20, v39, 63
	s_nop 1
	v_add_f32_e32 v39, s20, v184
	v_cmp_gt_f32_e32 vcc, s72, v39
	v_mul_f32_e32 v40, 0x4b800000, v39
	s_nop 0
	v_cndmask_b32_e32 v39, v39, v40, vcc
	v_rsq_f32_e32 v39, v39
	s_nop 0
	v_mul_f32_e32 v40, 0x45800000, v39
	v_cndmask_b32_e32 v39, v39, v40, vcc
	v_mul_f32_e32 v38, v38, v39
	v_add_f32_e32 v39, -1.0, v37
	v_fma_f32 v39, v79, v39, 1.0
	v_mul_f32_e32 v2, v2, v39
	v_mul_f32_e32 v3, v3, v2
	v_mul_f32_e32 v39, v78, v3
	ds_write2st64_b32 v1, v38, v36 offset1:16
	s_nop 0
	v_mov_b32_dpp v39, v39 quad_perm:[1,0,3,2] row_mask:0xf bank_mask:0xf bound_ctrl:1
	v_fmac_f32_e32 v39, v78, v3
	s_nop 1
	v_add_f32_dpp v3, v39, v39 quad_perm:[2,3,0,1] row_mask:0xf bank_mask:0xf bound_ctrl:1
	v_mov_b32_e32 v39, v0
	s_nop 0
	v_add_f32_dpp v3, v3, v3 row_half_mirror row_mask:0xf bank_mask:0xf bound_ctrl:1
	s_nop 1
	v_add_f32_dpp v3, v3, v3 row_mirror row_mask:0xf bank_mask:0xf bound_ctrl:1
	s_nop 1
	v_add_f32_dpp v3, v3, v3 row_bcast:15 row_mask:0xa bank_mask:0xf
	s_nop 1
	v_add_f32_dpp v3, v3, v3 row_bcast:31 row_mask:0xc bank_mask:0xf
	s_nop 0
	v_readlane_b32 s23, v3, 63
	v_mul_f32_e32 v3, v37, v38
	ds_write2st64_b32 v1, v3, v2 offset0:32 offset1:48
	s_and_saveexec_b64 s[20:21], s[16:17]
	v_lshl_add_u32 v1, s22, 2, v146
	v_mov_b32_e32 v2, s23
	ds_write_b32 v1, v2
	s_or_b64 exec, exec, s[20:21]
